# speedup vs baseline: 1.0225x; 1.0225x over previous
; #define LAS __attribute__((address_space(3)))
; __device__ __forceinline__ KArgs kargs() { KArgs p = (KArgs)__builtin_amdgcn_kernarg_segment_ptr(); asm volatile("" : "+s"(p)); return p; }
; __device__ __forceinline__ unsigned xb_add(unsigned* p, unsigned v) { return __hip_atomic_fetch_add(p, v, __ATOMIC_RELAXED, __HIP_MEMORY_SCOPE_AGENT); }
; __device__ __forceinline__ unsigned xb_xcc_id() { return (unsigned)__builtin_amdgcn_s_getreg((3 << 11) | 20) & 0xFu; }
; __global__ void __launch_bounds__(NTHR, 2) fwd_megakernel(Args a_unused) {
;     extern __shared__ __attribute__((aligned(16))) unsigned char lds_raw[];
;     cg::grid_group grid = cg::this_grid();
;     LAS unsigned char* lds = (LAS unsigned char*)lds_raw;
;     const int bid = blockIdx.x, G = gridDim.x;
;     if (threadIdx.x < 4) ((LAS unsigned*)(lds + LDS_BAR_OFF))[threadIdx.x] = 0u;
;     __syncthreads();
;     if (threadIdx.x == 0) { KArgs kb_ = kargs(); (void)xb_add((unsigned*)(kb_->ws + WS_BAR) + XB_XCNT(xb_xcc_id()), 1u); }
_Z14fwd_megakernel4Args:
	s_mov_b64 s[40:41], s[0:1]
	s_add_u32 s0, s40, 0x108
	s_addc_u32 s1, s41, 0
	v_and_b32_e32 v234, 0x3ff, v0
	v_writelane_b32 v254, s0, 0
	v_cmp_gt_u32_e32 vcc, 4, v234
	s_nop 0
	v_writelane_b32 v254, s1, 1
	s_and_saveexec_b64 s[0:1], vcc
	v_lshl_add_u32 v1, v234, 2, 0
	v_add_u32_e32 v1, 0x23ff0, v1
	v_mov_b32_e32 v2, 0
	ds_write_b32 v1, v2
	s_or_b64 exec, exec, s[0:1]
	s_mov_b32 s27, 0
	v_cmp_eq_u32_e64 s[4:5], 0, v234
	s_waitcnt lgkmcnt(0)
	s_barrier
	s_and_saveexec_b64 s[0:1], s[4:5]
	s_cbranch_execz .LBB0_5
	s_mov_b64 s[6:7], exec
	v_mbcnt_lo_u32_b32 v1, s6, 0
	v_mbcnt_hi_u32_b32 v1, s7, v1
	s_mov_b64 s[8:9], s[40:41]
	v_cmp_eq_u32_e32 vcc, 0, v1
	s_getreg_b32 s3, hwreg(HW_REG_XCC_ID, 0, 4)
	s_and_b64 s[10:11], exec, vcc
	s_mov_b64 exec, s[10:11]
	s_cbranch_execz .LBB0_5
	s_load_dwordx2 s[8:9], s[8:9], 0x100
	s_lshl_b32 s3, s3, 8
	s_and_b32 s3, s3, 0xf00
	v_mov_b32_e32 v1, 0x12b90000
	s_waitcnt lgkmcnt(0)
	s_add_u32 s8, s8, s3
	s_addc_u32 s9, s9, 0
	s_bcnt1_i32_b64 s3, s[6:7]
	v_mov_b32_e32 v2, s3
	global_atomic_add v1, v2, s[8:9] offset:1024
	s_load_dwordx2 s[10:11], s[40:41], 0x100
	s_lshr_b32 s3, s3, 8
	s_add_i32 s3, s3, 1
	v_mov_b32_e32 v4, s3
	s_lshl_b32 s3, s2, 2
	s_add_u32 s3, s3, 0x12b93600
	v_mov_b32_e32 v3, s3
	s_waitcnt lgkmcnt(0)
	global_store_dword v3, v4, s[10:11] sc0 sc1

; __device__ __forceinline__ KArgs kargs() { KArgs p = (KArgs)__builtin_amdgcn_kernarg_segment_ptr(); asm volatile("" : "+s"(p)); return p; }
; #define XBAR() do { KArgs kb_ = kargs(); xcd_barrier((unsigned*)(kb_->ws + WS_BAR), (volatile LAS unsigned*)(lds + LDS_BAR_OFF)); } while (0)
; __global__ void __launch_bounds__(NTHR, 2) fwd_megakernel(Args a_unused) {
;     ...
;     const bool defer = (G == 256);
;     prologue(lds, bid, G, threadIdx.x, defer);
;     if (gridDim.y == 0x7fffffffu) grid.sync();
;     XBAR();
; #pragma unroll 1
;     for (int l = 0; l < DEPTH; ++l) {
; #pragma unroll 1
;         for (int f = 0; f < 2; ++f) {
; #pragma unroll 1
;             for (int rep = 0; rep < (EXP_GU ? 2 : 1); ++rep) {
;                 KArgs ka = kargs(); unsigned char* ws = ka->ws; unsigned char* wl = ws + (size_t)l * WL_SIZE;
;                 pg8::Gemm g{f == 0 ? WSP(u16, WS_HBP) : WSP(u16, WS_HB), (const u16*)(wl + (f == 0 ? O_GU1 : O_GU2)), M, NGU, D}; pg8::StaticOrder S; S.init(M, NGU, G, bid);
;                 PrepRstd<16> P{lds, f == 0 ? WSP(float, WS_PART0) : WSP(float, WS_PART1), 1.0f / D};
;                 EpiGU E{WSP(u16, WS_ACT), lds};
;                 pg8::gemm_phase<EpiGU, PrepRstd<16>>(lds, g, S, E, P);
;                 if (defer && l + 1 < DEPTH && bid >= 128) convert_layer(lds, l + 1, f, 2, bid - 128, 128, threadIdx.x);
.LBB0_191:
	v_writelane_b32 v254, s15, 28
	v_writelane_b32 v254, s14, 29
	s_nop 1
	v_writelane_b32 v254, s15, 30
	s_or_b64 exec, exec, s[6:7]
	s_cmpk_lt_i32 s2, 0x580
	s_cselect_b64 s[0:1], -1, 0
	v_writelane_b32 v254, s0, 16
	s_add_i32 s6, s2, 0xffffff80
	s_ashr_i32 s7, s6, 31
	v_writelane_b32 v254, s1, 17
	s_lshr_b32 s0, s3, 29
	s_add_i32 s0, s2, s0
	s_ashr_i32 s12, s0, 3
	s_and_b32 s0, s0, -8
	s_sub_i32 s10, s2, s0
	s_lshl_b32 s0, s6, 3
	v_writelane_b32 v254, s0, 0
	s_lshl_b64 s[0:1], s[6:7], 9
	v_writelane_b32 v254, s0, 31
	s_cmpk_lt_i32 s2, 0x100
	s_waitcnt lgkmcnt(0)
	v_writelane_b32 v254, s1, 32
	s_cselect_b64 s[0:1], -1, 0
	s_lshl_b32 s11, s10, 5
	s_barrier
; #define GSYNC() XBAR()
;     __host__ __device__ bool next(int i, Unit& u) const {
;         const long L = (long)i * G + c; if (L >= nwg) return false;
;         int wgid = (int)L; { const int q = nwg / NXCD, r = nwg % NXCD, xcd = wgid % NXCD, off = wgid / NXCD; wgid = (xcd < r ? xcd * (q + 1) : r * (q + 1) + (xcd - r) * q) + off; }
;         const int nig = WGM * nN, gid = wgid / nig, fm = gid * WGM, gsz = (nM - fm) < WGM ? (nM - fm) : WGM;
;         u.pm = fm + ((wgid % nig) % gsz); u.pn = (wgid % nig) / gsz; return true;
; __global__ void __launch_bounds__(NTHR, 2) fwd_megakernel(Args a_unused) {
;     ...
;                 KArgs ka = kargs(); unsigned char* ws = ka->ws; unsigned char* wl = ws + (size_t)l * WL_SIZE;
;                 pg8::Gemm g{f == 0 ? WSP(u16, WS_HBP) : WSP(u16, WS_HB), (const u16*)(wl + (f == 0 ? O_GU1 : O_GU2)), M, NGU, D}; pg8::StaticOrder S; S.init(M, NGU, G, bid);
;                 PrepRstd<16> P{lds, f == 0 ? WSP(float, WS_PART0) : WSP(float, WS_PART1), 1.0f / D};
;                 EpiGU E{WSP(u16, WS_ACT), lds};
;                 pg8::gemm_phase<EpiGU, PrepRstd<16>>(lds, g, S, E, P);
;                 if (defer && l + 1 < DEPTH && bid >= 128) convert_layer(lds, l + 1, f, 2, bid - 128, 128, threadIdx.x);
;             }
;             GSYNC();
;             {
;                 KArgs ka = kargs(); unsigned char* ws = ka->ws; unsigned char* wl = ws + (size_t)l * WL_SIZE;
;                 pg8::Gemm g{WSP(u16, WS_ACT), (const u16*)(wl + (f == 0 ? O_D1 : O_D2)), M, D, FF}; pg8::StaticOrder S; S.init(M, D, G, bid);
;                 EpiRes<false> E{f == 0 ? WSP(u16, WS_HBP) : WSP(u16, WS_HB), WSP(u16, WS_HB), WSP(float, WS_PART1), lds, 0.5f, -1};
;                 pg8::gemm_phase<EpiRes<false>, NoPrep>(lds, g, S, E, NoPrep{});
;             }
;             GSYNC();
;             if (f == 0) {
;                 {
;                     KArgs ka = kargs(); unsigned char* ws = ka->ws; unsigned char* wl = ws + (size_t)l * WL_SIZE;
;                     pg8::Gemm g{WSP(u16, WS_HB), (const u16*)(wl + O_WIN), M, INC, D}; pg8::StaticOrder S; S.init(M, INC, G, bid);
;                     PrepRstd<16> P{lds, WSP(float, WS_PART1), 1.0f / D};
;                     EpiBf<true> E{WSP(u16, WS_Z), INC, lds};
;                     pg8::gemm_phase<EpiBf<true>, PrepRstd<16>>(lds, g, S, E, P);
;                 }
;                 GSYNC();
;                 {
	s_load_dwordx2 s[100:101], s[40:41], 0x100
	v_and_b32_e32 v2, 63, v234
	v_lshlrev_b32_e32 v2, 4, v2
	v_and_b32_e32 v3, 16, v2
	v_add_u32_e32 v2, 0x12b93600, v2
	v_add_u32_e32 v3, 0x12b93600, v3
	s_waitcnt lgkmcnt(0)
	global_load_dwordx4 v[4:7], v2, s[100:101] sc1
	global_load_dwordx4 v[12:15], v3, s[100:101] sc1
	s_waitcnt vmcnt(0)
	v_xor_b32_e32 v12, v12, v4
	v_xor_b32_e32 v13, v13, v5
	v_xor_b32_e32 v14, v14, v6
	v_xor_b32_e32 v15, v15, v7
	v_or3_b32 v12, v12, v13, v14
	v_or_b32_e32 v12, v12, v15
	v_min_u32_e32 v4, v4, v5
	v_min3_u32 v4, v4, v6, v7
	v_cmp_ne_u32_e64 s[98:99], 0, v12
	v_cmp_eq_u32_e64 s[100:101], 0, v4
	s_nop 4
	s_or_b64 s[98:99], s[98:99], s[100:101]
	s_cmp_eq_u64 s[98:99], 0
	s_cselect_b32 s98, 1, 0
	v_writelane_b32 v254, s0, 6
	s_cmpk_lt_i32 s2, 0x200
	s_load_dwordx2 s[14:15], s[40:41], 0x108
	v_writelane_b32 v254, s1, 7
	s_cselect_b64 s[0:1], -1, 0
	s_lshl_b32 s13, s10, 6
	v_writelane_b32 v254, s0, 33
	s_cmpk_lt_i32 s2, 0x80
	s_movk_i32 s33, 0xb1
	v_writelane_b32 v254, s1, 34
	s_cselect_b64 s[0:1], -1, 0
	v_writelane_b32 v254, s0, 35
	s_lshl_b32 s16, s10, 4
	s_waitcnt lgkmcnt(0)
	s_mul_i32 s15, s15, s14
	v_writelane_b32 v254, s1, 36
	s_lshr_b32 s0, s14, 31
	s_add_i32 s0, s14, s0
	s_ashr_i32 s0, s0, 1
	s_add_i32 s17, s0, s2
	s_cmpk_gt_i32 s2, 0x7f
	s_cselect_b64 s[8:9], -1, 0
	s_and_b64 s[0:1], s[8:9], exec
	s_cselect_b32 s0, 0x80, 1
	v_writelane_b32 v254, s0, 37
	s_cselect_b32 s0, s6, 0x100000
	v_writelane_b32 v254, s0, 38
	s_load_dword s0, s[40:41], 0x110
	s_cmp_lt_i32 s10, 0
	s_cselect_b32 s21, s33, 0xb0
	s_mul_i32 s1, s10, 0x41
	s_mul_i32 s20, s10, 17
	s_waitcnt lgkmcnt(0)
	s_mul_i32 s15, s15, s0
	s_mul_i32 s0, s10, 33
	s_mul_i32 s10, s10, s21
	s_cselect_b32 s11, s0, s11
	s_cselect_b32 s13, s1, s13
	s_cselect_b32 s16, s20, s16
	s_add_i32 s10, s10, s12
	s_mul_hi_i32 s0, s10, 0x2e8ba2e9
	s_lshr_b32 s1, s0, 31
	s_ashr_i32 s0, s0, 4
	s_add_i32 s0, s0, s1
	s_mul_i32 s1, s0, 0x58
	s_sub_i32 s1, s10, s1
	s_lshl_b32 s20, s0, 2
	s_bfe_i32 s0, s1, 0x80000
	s_bfe_u32 s0, s0, 0x2000d
	s_add_i32 s10, s1, s0
	s_bfe_i32 s0, s10, 0x80000
	s_and_b32 s10, s10, 0xfc
	s_sub_i32 s1, s1, s10
	s_sext_i32_i16 s21, s0
	s_sext_i32_i8 s1, s1
	s_add_i32 s20, s20, s1
	s_ashr_i32 s1, s21, 2
	v_writelane_b32 v254, s1, 39
	s_mov_b32 s10, s20
	s_lshr_b32 s0, s21, 2
	s_ashr_i32 s21, s20, 31
	v_writelane_b32 v254, s10, 40
	s_lshl_b64 s[20:21], s[20:21], 19
	s_bfe_i64 s[0:1], s[0:1], 0x100000
	v_writelane_b32 v254, s11, 41
	v_writelane_b32 v254, s20, 42
	s_lshl_b64 s[0:1], s[0:1], 19
	s_and_b64 s[8:9], s[66:67], s[8:9]
	v_writelane_b32 v254, s21, 43
	v_writelane_b32 v254, s0, 44
	s_mov_b32 s63, 0
	v_mov_b32_e32 v1, 0
	v_writelane_b32 v254, s1, 45
	s_add_i32 s0, s11, s12
	s_ashr_i32 s1, s0, 31
	s_lshr_b32 s1, s1, 28
	s_add_i32 s1, s0, s1
	s_ashr_i32 s10, s1, 4
	s_and_b32 s1, s1, 0xfff0
	s_sub_i32 s1, s0, s1
	s_bfe_i32 s0, s1, 0x80000
	s_bfe_u32 s0, s0, 0x2000d
	s_add_i32 s11, s1, s0
	s_bfe_i32 s0, s11, 0x80000
	s_and_b32 s11, s11, 0xfc
	s_sub_i32 s1, s1, s11
	s_lshl_b32 s10, s10, 2
	s_sext_i32_i16 s20, s0
	s_sext_i32_i8 s1, s1
	s_add_i32 s22, s10, s1
	s_ashr_i32 s1, s20, 2
	v_writelane_b32 v254, s1, 10
	s_add_i32 s1, s13, s12
	s_ashr_i32 s10, s1, 31
	s_lshr_b32 s10, s10, 27
	s_add_i32 s10, s1, s10
	s_ashr_i32 s11, s10, 5
	s_and_b32 s10, s10, 0xffe0
	s_sub_i32 s1, s1, s10
	s_bfe_i32 s10, s1, 0x80000
	s_bfe_u32 s10, s10, 0x2000d
	s_add_i32 s13, s1, s10
	s_bfe_i32 s10, s13, 0x80000
	s_and_b32 s13, s13, 0xfc
	s_sub_i32 s1, s1, s13
	s_lshr_b32 s0, s20, 2
	s_lshl_b32 s11, s11, 2
	s_sext_i32_i16 s20, s10
	s_sext_i32_i8 s1, s1
	s_add_i32 s24, s11, s1
	s_ashr_i32 s1, s20, 2
	s_lshr_b32 s10, s20, 2
	v_writelane_b32 v254, s1, 46
	s_mov_b32 s20, s24
	s_ashr_i32 s25, s24, 31
	v_writelane_b32 v254, s20, 47
	s_bfe_i64 s[10:11], s[10:11], 0x100000
	s_lshl_b64 s[10:11], s[10:11], 19
	v_writelane_b32 v254, s21, 48
	s_lshl_b64 s[20:21], s[24:25], 19
	v_writelane_b32 v254, s20, 49
	s_add_i32 s1, s16, s12
	s_ashr_i32 s23, s22, 31
	v_writelane_b32 v254, s21, 50
	v_writelane_b32 v254, s10, 51
	v_mov_b32_e32 v230, 0x358637bd
	s_mov_b32 s35, 0x800000
	v_writelane_b32 v254, s11, 52
	s_ashr_i32 s10, s1, 31
	s_lshr_b32 s10, s10, 29
	s_add_i32 s10, s1, s10
	s_ashr_i32 s11, s10, 3
	s_and_b32 s10, s10, 0xfff8
	s_sub_i32 s1, s1, s10
	s_bfe_i32 s10, s1, 0x80000
	s_bfe_u32 s10, s10, 0x2000d
	s_add_i32 s12, s1, s10
	s_bfe_i32 s10, s12, 0x80000
	s_and_b32 s12, s12, 0xfc
	s_sub_i32 s1, s1, s12
	s_lshl_b32 s11, s11, 2
	s_sext_i32_i16 s13, s10
	s_sext_i32_i8 s1, s1
	s_add_i32 s20, s11, s1
	s_ashr_i32 s1, s13, 2
	v_writelane_b32 v254, s1, 53
	v_writelane_b32 v254, s8, 54
	s_mov_b32 s12, s22
	s_lshr_b32 s10, s13, 2
	v_writelane_b32 v254, s9, 55
	s_abs_i32 s8, s14
	v_cvt_f32_u32_e32 v0, s8
	v_writelane_b32 v254, s12, 8
	s_bfe_i64 s[0:1], s[0:1], 0x100000
	s_lshl_b64 s[0:1], s[0:1], 19
	v_rcp_iflag_f32_e32 v0, v0
	v_writelane_b32 v254, s13, 9
	s_lshl_b64 s[12:13], s[22:23], 19
	v_writelane_b32 v254, s12, 56
	v_mul_f32_e32 v0, 0x4f7ffffe, v0
	v_cvt_u32_f32_e32 v0, v0
	v_writelane_b32 v254, s13, 57
	v_writelane_b32 v254, s0, 58
	s_ashr_i32 s21, s20, 31
	s_sub_i32 s9, 0, s8
	v_writelane_b32 v254, s1, 59
	s_mov_b32 s0, s20
	v_writelane_b32 v254, s0, 60
	s_mov_b32 s22, 0x10000
	s_mov_b32 s23, 0x16000
	v_writelane_b32 v254, s1, 61
	s_lshl_b64 s[0:1], s[20:21], 13
	v_writelane_b32 v254, s0, 62
	s_movk_i32 s37, 0x1600
	s_mov_b32 s50, 0x26000
	v_writelane_b32 v254, s1, 63
	s_bfe_i64 s[0:1], s[10:11], 0x100000
	v_readfirstlane_b32 s10, v0
	s_lshl_b64 s[0:1], s[0:1], 18
	s_mul_i32 s9, s9, s10
	v_writelane_b32 v255, s0, 0
	s_mul_hi_u32 s9, s10, s9
	s_add_i32 s10, s10, s9
	v_writelane_b32 v255, s1, 1
	s_abs_i32 s1, s17
	s_mul_hi_u32 s9, s1, s10
	s_mul_i32 s9, s9, s8
	s_sub_i32 s1, s1, s9
	s_ashr_i32 s0, s17, 31
	s_sub_i32 s9, s1, s8
	s_cmp_ge_u32 s1, s8
	s_cselect_b32 s1, s9, s1
	s_sub_i32 s9, s1, s8
	s_cmp_ge_u32 s1, s8
	s_cselect_b32 s1, s9, s1
	s_xor_b32 s1, s1, s0
	s_sub_i32 s0, s1, s0
	v_writelane_b32 v255, s0, 2
	s_lshl_b64 s[0:1], s[6:7], 13
	v_writelane_b32 v255, s0, 3
	s_lshl_b32 s39, s14, 2
	v_mov_b64_e32 v[232:233], 0x57f
	v_writelane_b32 v255, s1, 4
	s_lshl_b64 s[0:1], s[6:7], 14
	v_writelane_b32 v255, s0, 5
	v_mov_b64_e32 v[236:237], 0x580
	v_mov_b64_e32 v[240:241], 0x100
	v_writelane_b32 v255, s1, 6
	s_lshl_b32 s0, s2, 2
	v_writelane_b32 v255, s0, 7
	s_add_i32 s0, 0, 0x20000
	v_writelane_b32 v254, s0, 12
	s_add_i32 s0, 0, 0x23ff0
	v_writelane_b32 v254, s0, 26
	s_add_i32 s0, 0, 0x23ff4
	v_mov_b64_e32 v[242:243], 0xff
	v_mbcnt_hi_u32_b32 v231, -1, v42
	v_mov_b64_e32 v[244:245], 0x1ff
	s_mov_b32 s51, 0x2c000
	s_mov_b32 s52, 0x3c000
	s_movk_i32 s38, 0x5000
	s_mov_b32 s36, 0xb000
	s_mov_b32 s53, 0x1b000
	v_writelane_b32 v254, s0, 24
	s_add_i32 s34, 0, 0x11100
	s_mov_b64 s[64:65], 0x40000
	s_mov_b64 s[66:67], 0x80
	s_mov_b64 s[68:69], 0x100
	s_mov_b64 s[72:73], 0x200000
	s_mov_b64 s[74:75], 0x800000
	s_mov_b64 s[80:81], 0x180
	s_mov_b32 s82, s63
	s_branch .LBB0_193

; __device__ __forceinline__ unsigned xb_ld(unsigned* p)              { return __hip_atomic_load(p, __ATOMIC_RELAXED, __HIP_MEMORY_SCOPE_AGENT); }
; __device__ __forceinline__ unsigned xb_add(unsigned* p, unsigned v) { return __hip_atomic_fetch_add(p, v, __ATOMIC_RELAXED, __HIP_MEMORY_SCOPE_AGENT); }
; #define XB_SPIN(cond, bar) do { unsigned _sp = 0; while (cond) { __builtin_amdgcn_s_sleep(1); \
;     if ((++_sp & 255u) == 0u) { if (xb_ld(&(bar)[XB_TMO])) break; if (_sp > XB_SPIN_CAP) { atomicAdd(&(bar)[XB_TMO], 1u); break; } } } } while (0)
; __device__ __forceinline__ void xcd_barrier(unsigned* bar, volatile LAS unsigned* st) {
;     ...
;         const unsigned old = xb_add(&bar[XB_XSUB(x)], 1u);
;         const unsigned gen = old / nloc;
;         if (old + 1u == (gen + 1u) * nloc) {
;             __builtin_amdgcn_fence(__ATOMIC_RELEASE, "agent");
;             asm volatile("s_waitcnt vmcnt(0)" ::: "memory");
;             const unsigned og = xb_add(&bar[XB_TOP], 1u);
;             const unsigned tg = og / nx;
;             if (og + 1u == (tg + 1u) * nx) xb_add(&bar[XB_TOPGEN], 1u);
;             else XB_SPIN(xb_ld(&bar[XB_TOPGEN]) == tg, bar);
;             xb_add(&bar[XB_XGEN(x)], 1u);
;             __builtin_amdgcn_fence(__ATOMIC_ACQUIRE, "agent");
;             asm volatile("s_waitcnt vmcnt(0)" ::: "memory");
.LBB0_342:
	s_andn2_saveexec_b64 s[10:11], s[10:11]
	s_cbranch_execz .LBB0_362
	s_mov_b64 s[12:13], exec
	s_waitcnt lgkmcnt(0)
	s_cmp_lg_u32 s98, 0
	s_cbranch_scc1 .Lxl_skip_gu
	buffer_wbl2 sc1
	s_waitcnt vmcnt(0)
	v_mbcnt_lo_u32_b32 v2, s12, 0
	v_mbcnt_hi_u32_b32 v2, s13, v2
	v_cmp_eq_u32_e32 vcc, 0, v2
	s_and_saveexec_b64 s[16:17], vcc
	s_cbranch_execz .LBB0_345
	s_bcnt1_i32_b64 s12, s[12:13]
	v_mov_b32_e32 v3, s12
	v_mov_b32_e32 v4, 0x12b93000
	global_atomic_add v3, v4, v3, s[6:7] offset:1024 sc0

; __device__ __forceinline__ unsigned xb_ld(unsigned* p)              { return __hip_atomic_load(p, __ATOMIC_RELAXED, __HIP_MEMORY_SCOPE_AGENT); }
; __device__ __forceinline__ unsigned xb_add(unsigned* p, unsigned v) { return __hip_atomic_fetch_add(p, v, __ATOMIC_RELAXED, __HIP_MEMORY_SCOPE_AGENT); }
; #define XB_SPIN(cond, bar) do { unsigned _sp = 0; while (cond) { __builtin_amdgcn_s_sleep(1); \
;     if ((++_sp & 255u) == 0u) { if (xb_ld(&(bar)[XB_TMO])) break; if (_sp > XB_SPIN_CAP) { atomicAdd(&(bar)[XB_TMO], 1u); break; } } } } while (0)
; __device__ __forceinline__ void xcd_barrier(unsigned* bar, volatile LAS unsigned* st) {
;     ...
;             if (og + 1u == (tg + 1u) * nx) xb_add(&bar[XB_TOPGEN], 1u);
;             else XB_SPIN(xb_ld(&bar[XB_TOPGEN]) == tg, bar);
;             xb_add(&bar[XB_XGEN(x)], 1u);
;             __builtin_amdgcn_fence(__ATOMIC_ACQUIRE, "agent");
;             asm volatile("s_waitcnt vmcnt(0)" ::: "memory");
.Lxl_skip_gu:
	s_mov_b64 s[12:13], exec
	v_mbcnt_lo_u32_b32 v0, s12, 0
	v_mbcnt_hi_u32_b32 v0, s13, v0
	v_cmp_eq_u32_e32 vcc, 0, v0
	s_and_saveexec_b64 s[6:7], vcc
	s_cbranch_execz .LBB0_361
	s_bcnt1_i32_b64 s12, s[12:13]
	v_mov_b32_e32 v0, s12
	v_mov_b32_e32 v2, 0x2000
	global_atomic_add v2, v0, s[8:9] offset:1024

; __device__ __forceinline__ unsigned xb_ld(unsigned* p)              { return __hip_atomic_load(p, __ATOMIC_RELAXED, __HIP_MEMORY_SCOPE_AGENT); }
; __device__ __forceinline__ unsigned xb_add(unsigned* p, unsigned v) { return __hip_atomic_fetch_add(p, v, __ATOMIC_RELAXED, __HIP_MEMORY_SCOPE_AGENT); }
; #define XB_SPIN(cond, bar) do { unsigned _sp = 0; while (cond) { __builtin_amdgcn_s_sleep(1); \
;     if ((++_sp & 255u) == 0u) { if (xb_ld(&(bar)[XB_TMO])) break; if (_sp > XB_SPIN_CAP) { atomicAdd(&(bar)[XB_TMO], 1u); break; } } } } while (0)
; __device__ __forceinline__ void xcd_barrier(unsigned* bar, volatile LAS unsigned* st) {
;     ...
;         const unsigned old = xb_add(&bar[XB_XSUB(x)], 1u);
;         const unsigned gen = old / nloc;
;         if (old + 1u == (gen + 1u) * nloc) {
;             __builtin_amdgcn_fence(__ATOMIC_RELEASE, "agent");
;             asm volatile("s_waitcnt vmcnt(0)" ::: "memory");
;             const unsigned og = xb_add(&bar[XB_TOP], 1u);
;             const unsigned tg = og / nx;
;             if (og + 1u == (tg + 1u) * nx) xb_add(&bar[XB_TOPGEN], 1u);
;             else XB_SPIN(xb_ld(&bar[XB_TOPGEN]) == tg, bar);
;             xb_add(&bar[XB_XGEN(x)], 1u);
;             __builtin_amdgcn_fence(__ATOMIC_ACQUIRE, "agent");
;             asm volatile("s_waitcnt vmcnt(0)" ::: "memory");
.LBB0_435:
	s_andn2_saveexec_b64 s[12:13], s[16:17]
	s_cbranch_execz .LBB0_455
	s_mov_b64 s[12:13], exec
	s_waitcnt lgkmcnt(0)
	s_and_b32 s99, s98, s92
	s_cbranch_scc1 .Lxl_skip_d
	buffer_wbl2 sc1
	s_waitcnt vmcnt(0)
	v_mbcnt_lo_u32_b32 v0, s12, 0
	v_mbcnt_hi_u32_b32 v0, s13, v0
	v_cmp_eq_u32_e32 vcc, 0, v0
	s_and_saveexec_b64 s[16:17], vcc
	s_cbranch_execz .LBB0_438
	s_bcnt1_i32_b64 s12, s[12:13]
	v_mov_b32_e32 v3, s12
	v_mov_b32_e32 v4, 0x12b93000
	global_atomic_add v3, v4, v3, s[8:9] offset:1024 sc0

; __device__ __forceinline__ unsigned xb_ld(unsigned* p)              { return __hip_atomic_load(p, __ATOMIC_RELAXED, __HIP_MEMORY_SCOPE_AGENT); }
; __device__ __forceinline__ unsigned xb_add(unsigned* p, unsigned v) { return __hip_atomic_fetch_add(p, v, __ATOMIC_RELAXED, __HIP_MEMORY_SCOPE_AGENT); }
; #define XB_SPIN(cond, bar) do { unsigned _sp = 0; while (cond) { __builtin_amdgcn_s_sleep(1); \
;     if ((++_sp & 255u) == 0u) { if (xb_ld(&(bar)[XB_TMO])) break; if (_sp > XB_SPIN_CAP) { atomicAdd(&(bar)[XB_TMO], 1u); break; } } } } while (0)
; __device__ __forceinline__ void xcd_barrier(unsigned* bar, volatile LAS unsigned* st) {
;     ...
;             if (og + 1u == (tg + 1u) * nx) xb_add(&bar[XB_TOPGEN], 1u);
;             else XB_SPIN(xb_ld(&bar[XB_TOPGEN]) == tg, bar);
;             xb_add(&bar[XB_XGEN(x)], 1u);
;             __builtin_amdgcn_fence(__ATOMIC_ACQUIRE, "agent");
;             asm volatile("s_waitcnt vmcnt(0)" ::: "memory");
.Lxl_skip_d:
	s_mov_b64 s[12:13], exec
	v_mbcnt_lo_u32_b32 v0, s12, 0
	v_mbcnt_hi_u32_b32 v0, s13, v0
	v_cmp_eq_u32_e32 vcc, 0, v0
	s_and_saveexec_b64 s[8:9], vcc
	s_cbranch_execz .LBB0_454
	s_bcnt1_i32_b64 s12, s[12:13]
	v_mov_b32_e32 v0, s12
	v_mov_b32_e32 v2, 0x2000
	global_atomic_add v2, v0, s[10:11] offset:1024

; __device__ __forceinline__ unsigned xb_ld(unsigned* p)              { return __hip_atomic_load(p, __ATOMIC_RELAXED, __HIP_MEMORY_SCOPE_AGENT); }
; __device__ __forceinline__ unsigned xb_add(unsigned* p, unsigned v) { return __hip_atomic_fetch_add(p, v, __ATOMIC_RELAXED, __HIP_MEMORY_SCOPE_AGENT); }
; #define XB_SPIN(cond, bar) do { unsigned _sp = 0; while (cond) { __builtin_amdgcn_s_sleep(1); \
;     if ((++_sp & 255u) == 0u) { if (xb_ld(&(bar)[XB_TMO])) break; if (_sp > XB_SPIN_CAP) { atomicAdd(&(bar)[XB_TMO], 1u); break; } } } } while (0)
; __device__ __forceinline__ void xcd_barrier(unsigned* bar, volatile LAS unsigned* st) {
;     ...
;         const unsigned old = xb_add(&bar[XB_XSUB(x)], 1u);
;         const unsigned gen = old / nloc;
;         if (old + 1u == (gen + 1u) * nloc) {
;             __builtin_amdgcn_fence(__ATOMIC_RELEASE, "agent");
;             asm volatile("s_waitcnt vmcnt(0)" ::: "memory");
;             const unsigned og = xb_add(&bar[XB_TOP], 1u);
;             const unsigned tg = og / nx;
;             if (og + 1u == (tg + 1u) * nx) xb_add(&bar[XB_TOPGEN], 1u);
;             else XB_SPIN(xb_ld(&bar[XB_TOPGEN]) == tg, bar);
;             xb_add(&bar[XB_XGEN(x)], 1u);
;             __builtin_amdgcn_fence(__ATOMIC_ACQUIRE, "agent");
;             asm volatile("s_waitcnt vmcnt(0)" ::: "memory");
.LBB0_820:
	s_andn2_saveexec_b64 s[12:13], s[16:17]
	s_cbranch_execz .LBB0_840
	s_mov_b64 s[12:13], exec
	s_waitcnt lgkmcnt(0)
	s_cmp_lg_u32 s98, 0
	s_cbranch_scc1 .Lxl_skip_glu
	buffer_wbl2 sc1
	s_waitcnt vmcnt(0)
	v_mbcnt_lo_u32_b32 v0, s12, 0
	v_mbcnt_hi_u32_b32 v0, s13, v0
	v_cmp_eq_u32_e32 vcc, 0, v0
	s_and_saveexec_b64 s[16:17], vcc
	s_cbranch_execz .LBB0_823
	s_bcnt1_i32_b64 s12, s[12:13]
	v_mov_b32_e32 v3, s12
	v_mov_b32_e32 v4, 0x12b93000
	global_atomic_add v3, v4, v3, s[8:9] offset:1024 sc0

; __global__ void __launch_bounds__(NTHR, 2) fwd_megakernel(Args a_unused) {
;     extern __shared__ __attribute__((aligned(16))) unsigned char lds_raw[];
	.amdhsa_kernel _Z14fwd_megakernel4Args
		.amdhsa_group_segment_fixed_size 0
		.amdhsa_private_segment_fixed_size 0
		.amdhsa_kernarg_size 520
		.amdhsa_user_sgpr_count 2
		.amdhsa_user_sgpr_dispatch_ptr 0
		.amdhsa_user_sgpr_queue_ptr 0
		.amdhsa_user_sgpr_kernarg_segment_ptr 1
		.amdhsa_user_sgpr_dispatch_id 0
		.amdhsa_user_sgpr_kernarg_preload_length 0
		.amdhsa_user_sgpr_kernarg_preload_offset 0
		.amdhsa_user_sgpr_private_segment_size 0
		.amdhsa_uses_dynamic_stack 0
		.amdhsa_enable_private_segment 0
		.amdhsa_system_sgpr_workgroup_id_x 1
		.amdhsa_system_sgpr_workgroup_id_y 0
		.amdhsa_system_sgpr_workgroup_id_z 0
		.amdhsa_system_sgpr_workgroup_info 0
		.amdhsa_system_vgpr_workitem_id 2
		.amdhsa_next_free_vgpr 256
		.amdhsa_next_free_sgpr 102
		.amdhsa_accum_offset 256
		.amdhsa_reserve_vcc 1
		.amdhsa_float_round_mode_32 0
		.amdhsa_float_round_mode_16_64 0
		.amdhsa_float_denorm_mode_32 3
		.amdhsa_float_denorm_mode_16_64 3
		.amdhsa_dx10_clamp 1
		.amdhsa_ieee_mode 1
		.amdhsa_fp16_overflow 0
		.amdhsa_tg_split 0
		.amdhsa_exception_fp_ieee_invalid_op 0
		.amdhsa_exception_fp_denorm_src 0
		.amdhsa_exception_fp_ieee_div_zero 0
		.amdhsa_exception_fp_ieee_overflow 0
		.amdhsa_exception_fp_ieee_underflow 0
		.amdhsa_exception_fp_ieee_inexact 0
		.amdhsa_exception_int_div_zero 0
	.end_amdhsa_kernel

; __global__ void __launch_bounds__(NTHR, 2) fwd_megakernel(Args a_unused) {
;     extern __shared__ __attribute__((aligned(16))) unsigned char lds_raw[];
amdhsa.kernels:
  - .agpr_count:     0
    .args:
      - .offset:         0
        .size:           264
        .value_kind:     by_value
      - .offset:         264
        .size:           4
        .value_kind:     hidden_block_count_x
      - .offset:         268
        .size:           4
        .value_kind:     hidden_block_count_y
      - .offset:         272
        .size:           4
        .value_kind:     hidden_block_count_z
      - .offset:         276
        .size:           2
        .value_kind:     hidden_group_size_x
      - .offset:         278
        .size:           2
        .value_kind:     hidden_group_size_y
      - .offset:         280
        .size:           2
        .value_kind:     hidden_group_size_z
      - .offset:         282
        .size:           2
        .value_kind:     hidden_remainder_x
      - .offset:         284
        .size:           2
        .value_kind:     hidden_remainder_y
      - .offset:         286
        .size:           2
        .value_kind:     hidden_remainder_z
      - .offset:         304
        .size:           8
        .value_kind:     hidden_global_offset_x
      - .offset:         312
        .size:           8
        .value_kind:     hidden_global_offset_y
      - .offset:         320
        .size:           8
        .value_kind:     hidden_global_offset_z
      - .offset:         328
        .size:           2
        .value_kind:     hidden_grid_dims
      - .offset:         352
        .size:           8
        .value_kind:     hidden_multigrid_sync_arg
      - .offset:         384
        .size:           4
        .value_kind:     hidden_dynamic_lds_size
    .group_segment_fixed_size: 0
    .kernarg_segment_align: 8
    .kernarg_segment_size: 520
    .language:       OpenCL C
    .language_version:
      - 2
      - 0
    .max_flat_workgroup_size: 512
    .name:           _Z14fwd_megakernel4Args
    .private_segment_fixed_size: 0
    .sgpr_count:     108
    .sgpr_spill_count: 102
    .symbol:         _Z14fwd_megakernel4Args.kd
    .uniform_work_group_size: 1
    .uses_dynamic_stack: false
    .vgpr_count:     256
    .vgpr_spill_count: 0
    .wavefront_size: 64
